# NA item scheduler: next-item atomic issued behind the first operand loads with its own result register (no exposed device-scope round trip per item)
# baseline (speedup 1.0000x reference)
.LBB0_1308:
	v_mov_b32_e32 v181, v165
	s_lshl_b32 s13, s18, 2
	s_and_b32 s13, s13, 0xfc
	s_ashr_i32 s12, s18, 9
	v_add_u32_e32 v1, s13, v49
	s_mul_i32 s13, s12, 0x4100
	v_lshlrev_b32_e32 v2, 6, v1
	v_add3_u32 v166, v174, s13, v2
	v_ashrrev_i32_e32 v167, 31, v166
	s_bfe_u32 s14, s18, 0x30006
	v_lshlrev_b64 v[2:3], 10, v[166:167]
	s_lshl_b32 s12, s12, 3
	v_lshl_add_u64 v[2:3], s[20:21], 0, v[2:3]
	s_lshl_b32 s18, s14, 7
	s_or_b32 s12, s12, s14
	s_lshl_b32 s45, s14, 6
	v_lshl_add_u64 v[2:3], v[2:3], 0, s[18:19]
	s_ashr_i32 s13, s12, 31
	s_mul_i32 s18, s12, 0x208000
	s_mul_hi_i32 s15, s12, 0x208000
	s_add_u32 s28, s35, s18
	s_addc_u32 s29, s36, s15
	s_add_u32 s30, s37, s18
	s_addc_u32 s31, s38, s15
	s_lshl_b64 s[12:13], s[12:13], 2
	s_add_u32 s12, s3, s12
	s_addc_u32 s13, s34, s13
	global_load_dword v4, v165, s[12:13]
	s_mul_i32 s12, s14, 0x3c000
	s_add_u32 s26, s39, s12
	s_addc_u32 s27, s40, 0
	s_lshl_b32 s12, s14, 2
	s_add_u32 s12, s16, s12
	s_addc_u32 s13, s17, 0
	v_mov_b32_e32 v35, v0
	global_load_dword v34, v175, s[12:13] offset:16
	v_cmp_lt_i32_e32 vcc, v179, v180
	v_bfe_u32 v167, v35, 5, 1
	v_lshlrev_b32_e32 v164, 4, v167
	v_lshl_add_u64 v[2:3], v[2:3], 0, v[164:165]
	global_load_dwordx4 v[68:71], v[2:3], off offset:32
	global_load_dwordx4 v[72:75], v[2:3], off
	global_load_dwordx4 v[76:79], v[2:3], off offset:96
	global_load_dwordx4 v[80:83], v[2:3], off offset:64
	v_cndmask_b32_e32 v2, v178, v179, vcc
	v_lshlrev_b32_e32 v182, 2, v2
	v_mov_b32_e32 v169, 0
	s_mov_b32 s46, 0
	v_mov_b32_e32 v185, 23
	v_mov_b32_e32 v168, 0
	v_mov_b32_e32 v186, 0
	v_mov_b32_e32 v187, 0
	v_mov_b32_e32 v188, 0
	v_mov_b32_e32 v189, 0
	v_mov_b32_e32 v190, 0
	v_mov_b32_e32 v191, 0
	v_mov_b32_e32 v192, 0
	v_mov_b32_e32 v193, 0
	v_mov_b32_e32 v194, 0
	v_mov_b32_e32 v195, 0
	v_mov_b32_e32 v196, 0
	v_mov_b32_e32 v197, 0
	v_mov_b32_e32 v198, 0
	v_mov_b32_e32 v199, 0
	v_mov_b32_e32 v200, 0
	s_waitcnt vmcnt(0)
	v_mul_f32_e32 v2, 0x4f800000, v4
	v_cmp_gt_f32_e32 vcc, s41, v4
	v_and_b32_e32 v5, 0xffff0000, v68
	s_nop 0
	v_cndmask_b32_e32 v36, v4, v2, vcc
	v_and_b32_e32 v4, 0xffff0000, v72
	v_lshlrev_b32_e32 v3, 16, v68
	v_lshlrev_b32_e32 v2, 16, v72
	v_and_b32_e32 v21, 0xffff0000, v76
	v_and_b32_e32 v20, 0xffff0000, v80
	v_pk_mul_f32 v[4:5], v[4:5], v[4:5]
	v_lshlrev_b32_e32 v7, 16, v69
	v_lshlrev_b32_e32 v6, 16, v73
	v_lshlrev_b32_e32 v19, 16, v76
	v_lshlrev_b32_e32 v18, 16, v80
	v_pk_mul_f32 v[20:21], v[20:21], v[20:21]
	v_pk_fma_f32 v[2:3], v[2:3], v[2:3], v[4:5]
	v_and_b32_e32 v9, 0xffff0000, v69
	v_and_b32_e32 v8, 0xffff0000, v73
	v_lshlrev_b32_e32 v23, 16, v77
	v_lshlrev_b32_e32 v22, 16, v81
	v_pk_fma_f32 v[4:5], v[18:19], v[18:19], v[20:21]
	v_pk_fma_f32 v[2:3], v[6:7], v[6:7], v[2:3]
	v_lshlrev_b32_e32 v11, 16, v70
	v_lshlrev_b32_e32 v10, 16, v74
	v_and_b32_e32 v25, 0xffff0000, v77
	v_and_b32_e32 v24, 0xffff0000, v81
	v_pk_fma_f32 v[4:5], v[22:23], v[22:23], v[4:5]
	v_pk_fma_f32 v[2:3], v[8:9], v[8:9], v[2:3]
	v_and_b32_e32 v13, 0xffff0000, v70
	v_and_b32_e32 v12, 0xffff0000, v74
	v_lshlrev_b32_e32 v27, 16, v78
	v_lshlrev_b32_e32 v26, 16, v82
	v_pk_fma_f32 v[4:5], v[24:25], v[24:25], v[4:5]
	v_pk_fma_f32 v[2:3], v[10:11], v[10:11], v[2:3]
	v_lshlrev_b32_e32 v15, 16, v71
	v_lshlrev_b32_e32 v14, 16, v75
	v_and_b32_e32 v29, 0xffff0000, v78
	v_and_b32_e32 v28, 0xffff0000, v82
	v_pk_fma_f32 v[4:5], v[26:27], v[26:27], v[4:5]
	v_pk_fma_f32 v[2:3], v[12:13], v[12:13], v[2:3]
	v_and_b32_e32 v17, 0xffff0000, v71
	v_and_b32_e32 v16, 0xffff0000, v75
	v_lshlrev_b32_e32 v31, 16, v79
	v_lshlrev_b32_e32 v30, 16, v83
	v_pk_fma_f32 v[4:5], v[28:29], v[28:29], v[4:5]
	v_pk_fma_f32 v[2:3], v[14:15], v[14:15], v[2:3]
	v_and_b32_e32 v33, 0xffff0000, v79
	v_and_b32_e32 v32, 0xffff0000, v83
	v_pk_fma_f32 v[4:5], v[30:31], v[30:31], v[4:5]
	v_pk_fma_f32 v[2:3], v[16:17], v[16:17], v[2:3]
	v_pk_fma_f32 v[4:5], v[32:33], v[32:33], v[4:5]
	v_add_f32_e32 v2, v2, v3
	v_add_f32_e32 v2, v2, v4
	v_and_b32_e32 v4, 63, v35
	v_lshlrev_b32_e32 v164, 4, v4
	global_load_dwordx4 v[100:103], v164, s[28:29]
	global_load_dwordx4 v[104:107], v164, s[28:29] offset:1024
	global_load_dwordx4 v[108:111], v164, s[28:29] offset:2048
	global_load_dwordx4 v[112:115], v164, s[28:29] offset:3072
	global_load_dwordx4 v[96:99], v164, s[30:31]
	global_load_dwordx4 v[88:91], v164, s[30:31] offset:1024
	global_load_dwordx4 v[92:95], v164, s[30:31] offset:2048
	global_load_dwordx4 v[84:87], v164, s[30:31] offset:3072
	v_add_f32_e32 v2, v2, v5
	ds_bpermute_b32 v3, v182, v2
	v_sqrt_f32_e32 v37, v36
	v_lshl_add_u64 v[170:171], s[28:29], 0, v[164:165]
	v_lshl_add_u64 v[172:173], s[30:31], 0, v[164:165]
	v_lshlrev_b32_e32 v164, 2, v164
	s_waitcnt lgkmcnt(0)
	v_add_f32_e32 v2, v2, v3
	v_mul_f32_e32 v3, 0x4f800000, v2
	v_cmp_gt_f32_e64 s[12:13], s41, v2
	v_add_u32_e32 v5, -1, v37
	v_fma_f32 v7, -v5, v37, v36
	v_cndmask_b32_e64 v2, v2, v3, s[12:13]
	v_sqrt_f32_e32 v3, v2
	v_cmp_ge_f32_e64 s[14:15], 0, v7
	v_add_u32_e32 v6, 1, v37
	v_fma_f32 v8, -v6, v37, v36
	v_add_u32_e32 v7, -1, v3
	v_add_u32_e32 v9, 1, v3
	v_fma_f32 v10, -v7, v3, v2
	v_cndmask_b32_e64 v5, v37, v5, s[14:15]
	v_fma_f32 v11, -v9, v3, v2
	v_cmp_ge_f32_e64 s[14:15], 0, v10
	v_mov_b32_e32 v18, v169
	v_mov_b32_e32 v19, v169
	v_cndmask_b32_e64 v3, v3, v7, s[14:15]
	v_cmp_lt_f32_e64 s[14:15], 0, v11
	v_mov_b32_e32 v20, v169
	v_mov_b32_e32 v21, v169
	v_cndmask_b32_e64 v3, v3, v9, s[14:15]
	v_mul_f32_e32 v7, 0x37800000, v3
	v_cndmask_b32_e64 v3, v3, v7, s[12:13]
	v_cmp_class_f32_e64 s[12:13], v2, v176
	v_mov_b32_e32 v22, v169
	v_mov_b32_e32 v23, v169
	v_cndmask_b32_e64 v2, v3, v2, s[12:13]
	v_cmp_lt_f32_e64 s[12:13], 0, v8
	v_mov_b32_e32 v24, v169
	v_mov_b32_e32 v25, v169
	v_cndmask_b32_e64 v3, v5, v6, s[12:13]
	v_mul_f32_e32 v5, 0x37800000, v3
	v_cndmask_b32_e32 v3, v3, v5, vcc
	v_cmp_class_f32_e32 vcc, v36, v176
	v_mov_b32_e32 v26, v169
	v_mov_b32_e32 v27, v169
	v_cndmask_b32_e32 v3, v3, v36, vcc
	v_mul_f32_e32 v2, v3, v2
	v_max_f32_e32 v3, v34, v34
	v_max_f32_e32 v34, 0, v3
	v_fmac_f32_e32 v34, 0x3f800347, v2
	v_med3_i32 v2, v1, 4, v177
	v_add_u32_e32 v2, -4, v2
	v_sub_u32_e32 v1, v2, v1
	v_xor_b32_e32 v36, 0x80000000, v34
	v_lshl_add_u32 v183, v2, 1, -8
	v_lshl_add_u32 v184, v1, 1, -8
	v_mov_b32_e32 v1, v34
	v_mov_b32_e32 v38, v34
	v_mov_b32_e32 v35, v34
	v_mov_b32_e32 v40, v34
	v_mov_b32_e32 v37, v34
	v_mov_b32_e32 v42, v34
	v_mov_b32_e32 v28, v169
	v_mov_b32_e32 v29, v169
	v_mov_b32_e32 v30, v169
	v_mov_b32_e32 v31, v169
	v_mov_b32_e32 v32, v169
	v_mov_b32_e32 v33, v169
	v_mov_b32_e32 v2, v169
	v_mov_b32_e32 v3, v169
	v_mov_b32_e32 v4, v169
	v_mov_b32_e32 v5, v169
	v_mov_b32_e32 v6, v169
	v_mov_b32_e32 v7, v169
	v_mov_b32_e32 v8, v169
	v_mov_b32_e32 v9, v169
	v_mov_b32_e32 v10, v169
	v_mov_b32_e32 v11, v169
	v_mov_b32_e32 v12, v169
	v_mov_b32_e32 v13, v169
	v_mov_b32_e32 v14, v169
	v_mov_b32_e32 v15, v169
	v_mov_b32_e32 v16, v169
	v_mov_b32_e32 v17, v169
	v_mov_b32_e32 v39, v34
	v_mov_b32_e32 v44, v34
	v_mov_b32_e32 v41, v34
	v_mov_b32_e32 v46, v34
	v_mov_b32_e32 v43, v34
	v_mov_b32_e32 v48, v34
	v_mov_b32_e32 v45, v34
	v_mov_b32_e32 v50, v34
	v_mov_b32_e32 v47, v34
	s_and_saveexec_b64 s[98:99], s[10:11]
	s_cbranch_execz .Lna_at0
	v_mov_b32_e32 v254, 1
	global_atomic_add v253, v165, v254, s[16:17] offset:32 sc0
.Lna_at0:
	s_or_b64 exec, exec, s[98:99]

.LBB0_1319:
	ds_bpermute_b32 v1, v182, v169
	v_mov_b64_e32 v[34:35], s[22:23]
	s_lshl_b32 s18, s45, 1
	v_mad_i64_i32 v[34:35], s[12:13], v166, s42, v[34:35]
	s_waitcnt lgkmcnt(0)
	v_add_f32_e32 v1, v169, v1
	v_div_scale_f32 v36, s[12:13], v1, v1, 1.0
	v_rcp_f32_e32 v37, v36
	v_lshl_add_u64 v[34:35], v[34:35], 0, s[18:19]
	v_lshlrev_b32_e32 v164, 3, v167
	v_lshl_add_u64 v[34:35], v[34:35], 0, v[164:165]
	v_fma_f32 v38, -v36, v37, 1.0
	v_fmac_f32_e32 v37, v38, v37
	v_div_scale_f32 v38, vcc, 1.0, v1, 1.0
	v_mul_f32_e32 v39, v38, v37
	v_fma_f32 v40, -v36, v39, v38
	v_fmac_f32_e32 v39, v40, v37
	v_fma_f32 v36, -v36, v39, v38
	v_div_fmas_f32 v36, v36, v37, v39
	v_div_fixup_f32 v36, v36, v1, 1.0
	v_pk_mul_f32 v[18:19], v[18:19], v[36:37] op_sel_hi:[1,0]
	v_pk_mul_f32 v[20:21], v[20:21], v[36:37] op_sel_hi:[1,0]
	v_pk_mul_f32 v[2:3], v[2:3], v[36:37] op_sel_hi:[1,0]
	v_pk_mul_f32 v[4:5], v[4:5], v[36:37] op_sel_hi:[1,0]
	v_cvt_pk_bf16_f32 v18, v18, v19
	v_cvt_pk_bf16_f32 v19, v20, v21
	v_cvt_pk_bf16_f32 v2, v2, v3
	v_cvt_pk_bf16_f32 v3, v4, v5
	global_store_dwordx2 v[34:35], v[18:19], off
	v_pk_mul_f32 v[18:19], v[22:23], v[36:37] op_sel_hi:[1,0]
	v_pk_mul_f32 v[20:21], v[24:25], v[36:37] op_sel_hi:[1,0]
	global_store_dwordx2 v[34:35], v[2:3], off offset:64
	v_pk_mul_f32 v[2:3], v[6:7], v[36:37] op_sel_hi:[1,0]
	v_pk_mul_f32 v[4:5], v[8:9], v[36:37] op_sel_hi:[1,0]
	v_cvt_pk_bf16_f32 v18, v18, v19
	v_cvt_pk_bf16_f32 v19, v20, v21
	v_cvt_pk_bf16_f32 v2, v2, v3
	v_cvt_pk_bf16_f32 v3, v4, v5
	global_store_dwordx2 v[34:35], v[18:19], off offset:16
	v_pk_mul_f32 v[18:19], v[26:27], v[36:37] op_sel_hi:[1,0]
	v_pk_mul_f32 v[20:21], v[28:29], v[36:37] op_sel_hi:[1,0]
	global_store_dwordx2 v[34:35], v[2:3], off offset:80
	v_pk_mul_f32 v[2:3], v[10:11], v[36:37] op_sel_hi:[1,0]
	v_pk_mul_f32 v[4:5], v[12:13], v[36:37] op_sel_hi:[1,0]
	v_cvt_pk_bf16_f32 v18, v18, v19
	v_cvt_pk_bf16_f32 v19, v20, v21
	v_cvt_pk_bf16_f32 v2, v2, v3
	v_cvt_pk_bf16_f32 v3, v4, v5
	global_store_dwordx2 v[34:35], v[18:19], off offset:32
	v_pk_mul_f32 v[18:19], v[30:31], v[36:37] op_sel_hi:[1,0]
	v_pk_mul_f32 v[20:21], v[32:33], v[36:37] op_sel_hi:[1,0]
	global_store_dwordx2 v[34:35], v[2:3], off offset:96
	v_pk_mul_f32 v[2:3], v[14:15], v[36:37] op_sel_hi:[1,0]
	v_pk_mul_f32 v[4:5], v[16:17], v[36:37] op_sel_hi:[1,0]
	v_cvt_pk_bf16_f32 v18, v18, v19
	v_cvt_pk_bf16_f32 v19, v20, v21
	v_cvt_pk_bf16_f32 v2, v2, v3
	v_cvt_pk_bf16_f32 v3, v4, v5
	global_store_dwordx2 v[34:35], v[18:19], off offset:48
	global_store_dwordx2 v[34:35], v[2:3], off offset:112
	s_and_saveexec_b64 s[12:13], s[10:11]
	s_cbranch_execz .LBB0_1307
	s_lshl_b32 s14, s44, 2
	s_add_i32 s14, s14, 0
	v_add_u32_e32 v1, s2, v253
	v_mov_b32_e32 v2, s14
	ds_write_b32 v2, v1
	s_branch .LBB0_1307

.LBB0_4080:
	v_mov_b32_e32 v181, v165
	s_lshl_b32 s2, s20, 2
	s_ashr_i32 s0, s20, 9
	s_and_b32 s2, s2, 0xfc
	s_bfe_u32 s1, s20, 0x30006
	v_add_u32_e32 v1, s2, v49
	s_mul_i32 s2, s0, 0x4100
	s_lshl_b32 s0, s0, 3
	v_lshlrev_b32_e32 v2, 6, v1
	s_or_b32 s14, s0, s1
	v_add3_u32 v166, v174, s2, v2
	s_lshl_b32 s43, s1, 6
	s_lshl_b32 s20, s1, 7
	s_ashr_i32 s15, s14, 31
	s_mul_i32 s2, s14, 0x208000
	s_mul_hi_i32 s0, s14, 0x208000
	s_add_u32 s28, s35, s2
	s_addc_u32 s29, s36, s0
	s_add_u32 s30, s37, s2
	s_addc_u32 s31, s38, s0
	s_lshl_b64 s[14:15], s[14:15], 2
	s_add_u32 s14, s3, s14
	s_addc_u32 s15, s34, s15
	s_mul_i32 s0, s1, 0x3c000
	s_add_u32 s0, s18, s0
	s_addc_u32 s2, s19, 0
	s_add_u32 s26, s0, 0x223100
	s_addc_u32 s27, s2, 0
	s_lshl_b32 s0, s1, 2
	v_ashrrev_i32_e32 v167, 31, v166
	global_load_dword v4, v165, s[14:15]
	s_add_u32 s14, s18, s0
	v_lshlrev_b64 v[2:3], 10, v[166:167]
	s_addc_u32 s15, s19, 0
	v_mov_b32_e32 v35, v0
	v_lshl_add_u64 v[2:3], s[22:23], 0, v[2:3]
	global_load_dword v34, v175, s[14:15] offset:48
	v_lshl_add_u64 v[2:3], v[2:3], 0, s[20:21]
	v_bfe_u32 v167, v35, 5, 1
	v_lshlrev_b32_e32 v164, 4, v167
	v_lshl_add_u64 v[2:3], v[2:3], 0, v[164:165]
	global_load_dwordx4 v[68:71], v[2:3], off offset:32
	global_load_dwordx4 v[72:75], v[2:3], off
	global_load_dwordx4 v[76:79], v[2:3], off offset:96
	global_load_dwordx4 v[80:83], v[2:3], off offset:64
	v_cmp_lt_i32_e32 vcc, v179, v180
	v_mov_b32_e32 v169, 0
	s_mov_b32 s44, 0
	v_cndmask_b32_e32 v2, v178, v179, vcc
	v_lshlrev_b32_e32 v182, 2, v2
	v_mov_b32_e32 v185, 23
	v_mov_b32_e32 v168, 0
	v_mov_b32_e32 v186, 0
	v_mov_b32_e32 v187, 0
	v_mov_b32_e32 v188, 0
	v_mov_b32_e32 v189, 0
	v_mov_b32_e32 v190, 0
	v_mov_b32_e32 v191, 0
	v_mov_b32_e32 v192, 0
	v_mov_b32_e32 v193, 0
	v_mov_b32_e32 v194, 0
	v_mov_b32_e32 v195, 0
	v_mov_b32_e32 v196, 0
	v_mov_b32_e32 v197, 0
	v_mov_b32_e32 v198, 0
	v_mov_b32_e32 v199, 0
	v_mov_b32_e32 v200, 0
	s_waitcnt vmcnt(0)
	v_mul_f32_e32 v2, 0x4f800000, v4
	v_cmp_gt_f32_e32 vcc, s39, v4
	v_and_b32_e32 v5, 0xffff0000, v68
	s_nop 0
	v_cndmask_b32_e32 v36, v4, v2, vcc
	v_and_b32_e32 v4, 0xffff0000, v72
	v_lshlrev_b32_e32 v3, 16, v68
	v_lshlrev_b32_e32 v2, 16, v72
	v_and_b32_e32 v21, 0xffff0000, v76
	v_and_b32_e32 v20, 0xffff0000, v80
	v_pk_mul_f32 v[4:5], v[4:5], v[4:5]
	v_lshlrev_b32_e32 v7, 16, v69
	v_lshlrev_b32_e32 v6, 16, v73
	v_lshlrev_b32_e32 v19, 16, v76
	v_lshlrev_b32_e32 v18, 16, v80
	v_pk_mul_f32 v[20:21], v[20:21], v[20:21]
	v_pk_fma_f32 v[2:3], v[2:3], v[2:3], v[4:5]
	v_and_b32_e32 v9, 0xffff0000, v69
	v_and_b32_e32 v8, 0xffff0000, v73
	v_lshlrev_b32_e32 v23, 16, v77
	v_lshlrev_b32_e32 v22, 16, v81
	v_pk_fma_f32 v[4:5], v[18:19], v[18:19], v[20:21]
	v_pk_fma_f32 v[2:3], v[6:7], v[6:7], v[2:3]
	v_lshlrev_b32_e32 v11, 16, v70
	v_lshlrev_b32_e32 v10, 16, v74
	v_and_b32_e32 v25, 0xffff0000, v77
	v_and_b32_e32 v24, 0xffff0000, v81
	v_pk_fma_f32 v[4:5], v[22:23], v[22:23], v[4:5]
	v_pk_fma_f32 v[2:3], v[8:9], v[8:9], v[2:3]
	v_and_b32_e32 v13, 0xffff0000, v70
	v_and_b32_e32 v12, 0xffff0000, v74
	v_lshlrev_b32_e32 v27, 16, v78
	v_lshlrev_b32_e32 v26, 16, v82
	v_pk_fma_f32 v[4:5], v[24:25], v[24:25], v[4:5]
	v_pk_fma_f32 v[2:3], v[10:11], v[10:11], v[2:3]
	v_lshlrev_b32_e32 v15, 16, v71
	v_lshlrev_b32_e32 v14, 16, v75
	v_and_b32_e32 v29, 0xffff0000, v78
	v_and_b32_e32 v28, 0xffff0000, v82
	v_pk_fma_f32 v[4:5], v[26:27], v[26:27], v[4:5]
	v_pk_fma_f32 v[2:3], v[12:13], v[12:13], v[2:3]
	v_and_b32_e32 v17, 0xffff0000, v71
	v_and_b32_e32 v16, 0xffff0000, v75
	v_lshlrev_b32_e32 v31, 16, v79
	v_lshlrev_b32_e32 v30, 16, v83
	v_pk_fma_f32 v[4:5], v[28:29], v[28:29], v[4:5]
	v_pk_fma_f32 v[2:3], v[14:15], v[14:15], v[2:3]
	v_and_b32_e32 v33, 0xffff0000, v79
	v_and_b32_e32 v32, 0xffff0000, v83
	v_pk_fma_f32 v[4:5], v[30:31], v[30:31], v[4:5]
	v_pk_fma_f32 v[2:3], v[16:17], v[16:17], v[2:3]
	v_pk_fma_f32 v[4:5], v[32:33], v[32:33], v[4:5]
	v_add_f32_e32 v2, v2, v3
	v_add_f32_e32 v2, v2, v4
	v_and_b32_e32 v4, 63, v35
	v_lshlrev_b32_e32 v164, 4, v4
	global_load_dwordx4 v[100:103], v164, s[28:29]
	global_load_dwordx4 v[104:107], v164, s[28:29] offset:1024
	global_load_dwordx4 v[108:111], v164, s[28:29] offset:2048
	global_load_dwordx4 v[112:115], v164, s[28:29] offset:3072
	global_load_dwordx4 v[96:99], v164, s[30:31]
	global_load_dwordx4 v[88:91], v164, s[30:31] offset:1024
	global_load_dwordx4 v[92:95], v164, s[30:31] offset:2048
	global_load_dwordx4 v[84:87], v164, s[30:31] offset:3072
	v_add_f32_e32 v2, v2, v5
	ds_bpermute_b32 v3, v182, v2
	v_sqrt_f32_e32 v37, v36
	v_lshl_add_u64 v[170:171], s[28:29], 0, v[164:165]
	v_lshl_add_u64 v[172:173], s[30:31], 0, v[164:165]
	v_lshlrev_b32_e32 v164, 2, v164
	s_waitcnt lgkmcnt(0)
	v_add_f32_e32 v2, v2, v3
	v_mul_f32_e32 v3, 0x4f800000, v2
	v_cmp_gt_f32_e64 s[14:15], s39, v2
	v_add_u32_e32 v5, -1, v37
	v_fma_f32 v7, -v5, v37, v36
	v_cndmask_b32_e64 v2, v2, v3, s[14:15]
	v_sqrt_f32_e32 v3, v2
	v_cmp_ge_f32_e64 s[16:17], 0, v7
	v_add_u32_e32 v6, 1, v37
	v_fma_f32 v8, -v6, v37, v36
	v_add_u32_e32 v7, -1, v3
	v_add_u32_e32 v9, 1, v3
	v_fma_f32 v10, -v7, v3, v2
	v_cndmask_b32_e64 v5, v37, v5, s[16:17]
	v_fma_f32 v11, -v9, v3, v2
	v_cmp_ge_f32_e64 s[16:17], 0, v10
	v_mov_b32_e32 v18, v169
	v_mov_b32_e32 v19, v169
	v_cndmask_b32_e64 v3, v3, v7, s[16:17]
	v_cmp_lt_f32_e64 s[16:17], 0, v11
	v_mov_b32_e32 v20, v169
	v_mov_b32_e32 v21, v169
	v_cndmask_b32_e64 v3, v3, v9, s[16:17]
	v_mul_f32_e32 v7, 0x37800000, v3
	v_cndmask_b32_e64 v3, v3, v7, s[14:15]
	v_cmp_class_f32_e64 s[14:15], v2, v176
	v_mov_b32_e32 v22, v169
	v_mov_b32_e32 v23, v169
	v_cndmask_b32_e64 v2, v3, v2, s[14:15]
	v_cmp_lt_f32_e64 s[14:15], 0, v8
	v_mov_b32_e32 v24, v169
	v_mov_b32_e32 v25, v169
	v_cndmask_b32_e64 v3, v5, v6, s[14:15]
	v_mul_f32_e32 v5, 0x37800000, v3
	v_cndmask_b32_e32 v3, v3, v5, vcc
	v_cmp_class_f32_e32 vcc, v36, v176
	v_mov_b32_e32 v26, v169
	v_mov_b32_e32 v27, v169
	v_cndmask_b32_e32 v3, v3, v36, vcc
	v_mul_f32_e32 v2, v3, v2
	v_max_f32_e32 v3, v34, v34
	v_max_f32_e32 v34, 0, v3
	v_fmac_f32_e32 v34, 0x3f800347, v2
	v_med3_i32 v2, v1, 4, v177
	v_add_u32_e32 v2, -4, v2
	v_sub_u32_e32 v1, v2, v1
	v_xor_b32_e32 v36, 0x80000000, v34
	v_lshl_add_u32 v183, v2, 1, -8
	v_lshl_add_u32 v184, v1, 1, -8
	v_mov_b32_e32 v1, v34
	v_mov_b32_e32 v38, v34
	v_mov_b32_e32 v35, v34
	v_mov_b32_e32 v40, v34
	v_mov_b32_e32 v37, v34
	v_mov_b32_e32 v42, v34
	v_mov_b32_e32 v28, v169
	v_mov_b32_e32 v29, v169
	v_mov_b32_e32 v30, v169
	v_mov_b32_e32 v31, v169
	v_mov_b32_e32 v32, v169
	v_mov_b32_e32 v33, v169
	v_mov_b32_e32 v2, v169
	v_mov_b32_e32 v3, v169
	v_mov_b32_e32 v4, v169
	v_mov_b32_e32 v5, v169
	v_mov_b32_e32 v6, v169
	v_mov_b32_e32 v7, v169
	v_mov_b32_e32 v8, v169
	v_mov_b32_e32 v9, v169
	v_mov_b32_e32 v10, v169
	v_mov_b32_e32 v11, v169
	v_mov_b32_e32 v12, v169
	v_mov_b32_e32 v13, v169
	v_mov_b32_e32 v14, v169
	v_mov_b32_e32 v15, v169
	v_mov_b32_e32 v16, v169
	v_mov_b32_e32 v17, v169
	v_mov_b32_e32 v39, v34
	v_mov_b32_e32 v44, v34
	v_mov_b32_e32 v41, v34
	v_mov_b32_e32 v46, v34
	v_mov_b32_e32 v43, v34
	v_mov_b32_e32 v48, v34
	v_mov_b32_e32 v45, v34
	v_mov_b32_e32 v50, v34
	v_mov_b32_e32 v47, v34
	s_and_saveexec_b64 s[98:99], s[12:13]
	s_cbranch_execz .Lna_at1
	v_mov_b32_e32 v254, 1
	global_atomic_add v253, v165, v254, s[18:19] offset:36 sc0

.LBB0_4091:
	ds_bpermute_b32 v1, v182, v169
	v_mov_b64_e32 v[34:35], s[24:25]
	s_lshl_b32 s20, s43, 1
	v_mad_i64_i32 v[34:35], s[14:15], v166, s40, v[34:35]
	s_waitcnt lgkmcnt(0)
	v_add_f32_e32 v1, v169, v1
	v_div_scale_f32 v36, s[14:15], v1, v1, 1.0
	v_rcp_f32_e32 v37, v36
	v_lshl_add_u64 v[34:35], v[34:35], 0, s[20:21]
	v_lshlrev_b32_e32 v164, 3, v167
	v_lshl_add_u64 v[34:35], v[34:35], 0, v[164:165]
	v_fma_f32 v38, -v36, v37, 1.0
	v_fmac_f32_e32 v37, v38, v37
	v_div_scale_f32 v38, vcc, 1.0, v1, 1.0
	v_mul_f32_e32 v39, v38, v37
	v_fma_f32 v40, -v36, v39, v38
	v_fmac_f32_e32 v39, v40, v37
	v_fma_f32 v36, -v36, v39, v38
	v_div_fmas_f32 v36, v36, v37, v39
	v_div_fixup_f32 v36, v36, v1, 1.0
	v_pk_mul_f32 v[18:19], v[18:19], v[36:37] op_sel_hi:[1,0]
	v_pk_mul_f32 v[20:21], v[20:21], v[36:37] op_sel_hi:[1,0]
	v_pk_mul_f32 v[2:3], v[2:3], v[36:37] op_sel_hi:[1,0]
	v_pk_mul_f32 v[4:5], v[4:5], v[36:37] op_sel_hi:[1,0]
	v_cvt_pk_bf16_f32 v18, v18, v19
	v_cvt_pk_bf16_f32 v19, v20, v21
	v_cvt_pk_bf16_f32 v2, v2, v3
	v_cvt_pk_bf16_f32 v3, v4, v5
	global_store_dwordx2 v[34:35], v[18:19], off
	v_pk_mul_f32 v[18:19], v[22:23], v[36:37] op_sel_hi:[1,0]
	v_pk_mul_f32 v[20:21], v[24:25], v[36:37] op_sel_hi:[1,0]
	global_store_dwordx2 v[34:35], v[2:3], off offset:64
	v_pk_mul_f32 v[2:3], v[6:7], v[36:37] op_sel_hi:[1,0]
	v_pk_mul_f32 v[4:5], v[8:9], v[36:37] op_sel_hi:[1,0]
	v_cvt_pk_bf16_f32 v18, v18, v19
	v_cvt_pk_bf16_f32 v19, v20, v21
	v_cvt_pk_bf16_f32 v2, v2, v3
	v_cvt_pk_bf16_f32 v3, v4, v5
	global_store_dwordx2 v[34:35], v[18:19], off offset:16
	v_pk_mul_f32 v[18:19], v[26:27], v[36:37] op_sel_hi:[1,0]
	v_pk_mul_f32 v[20:21], v[28:29], v[36:37] op_sel_hi:[1,0]
	global_store_dwordx2 v[34:35], v[2:3], off offset:80
	v_pk_mul_f32 v[2:3], v[10:11], v[36:37] op_sel_hi:[1,0]
	v_pk_mul_f32 v[4:5], v[12:13], v[36:37] op_sel_hi:[1,0]
	v_cvt_pk_bf16_f32 v18, v18, v19
	v_cvt_pk_bf16_f32 v19, v20, v21
	v_cvt_pk_bf16_f32 v2, v2, v3
	v_cvt_pk_bf16_f32 v3, v4, v5
	global_store_dwordx2 v[34:35], v[18:19], off offset:32
	v_pk_mul_f32 v[18:19], v[30:31], v[36:37] op_sel_hi:[1,0]
	v_pk_mul_f32 v[20:21], v[32:33], v[36:37] op_sel_hi:[1,0]
	global_store_dwordx2 v[34:35], v[2:3], off offset:96
	v_pk_mul_f32 v[2:3], v[14:15], v[36:37] op_sel_hi:[1,0]
	v_pk_mul_f32 v[4:5], v[16:17], v[36:37] op_sel_hi:[1,0]
	v_cvt_pk_bf16_f32 v18, v18, v19
	v_cvt_pk_bf16_f32 v19, v20, v21
	v_cvt_pk_bf16_f32 v2, v2, v3
	v_cvt_pk_bf16_f32 v3, v4, v5
	global_store_dwordx2 v[34:35], v[18:19], off offset:48
	global_store_dwordx2 v[34:35], v[2:3], off offset:112
	s_and_saveexec_b64 s[14:15], s[12:13]
	s_cbranch_execz .LBB0_4079
	s_lshl_b32 s0, s42, 2
	s_add_i32 s0, s0, 0
	v_add_u32_e32 v1, s52, v253
	v_mov_b32_e32 v2, s0
	ds_write_b32 v2, v1
	s_branch .LBB0_4079
